# diff-attn loop split into vector section and matrix section with two barriers per key tile, stream-2 wave group half an iteration behind; V/K/Q fragments prefetched two groups ahead; 4-way independent
# speedup vs baseline: 1.0535x; 1.0245x over previous
.LBB0_322:
	v_add_f32_e32 v16, 0, v16
	v_add_f32_e32 v32, 0, v32
	v_add_f32_e32 v16, v17, v16
	v_add_f32_e32 v17, v33, v32
	v_add_f32_e32 v16, v18, v16
	v_add_f32_e32 v17, v34, v17
	v_add_f32_e32 v16, v19, v16
	v_add_f32_e32 v17, v35, v17
	v_add_f32_e32 v16, v20, v16
	v_add_f32_e32 v17, v36, v17
	v_add_f32_e32 v16, v21, v16
	v_add_f32_e32 v17, v37, v17
	v_add_f32_e32 v16, v22, v16
	v_add_f32_e32 v17, v38, v17
	v_add_f32_e32 v16, v23, v16
	v_add_f32_e32 v17, v39, v17
	v_add_f32_e32 v16, v24, v16
	v_add_f32_e32 v17, v40, v17
	v_add_f32_e32 v16, v25, v16
	v_add_f32_e32 v17, v41, v17
	v_add_f32_e32 v16, v26, v16
	v_add_f32_e32 v17, v42, v17
	v_add_f32_e32 v16, v27, v16
	v_add_f32_e32 v17, v43, v17
	v_add_f32_e32 v16, v28, v16
	v_add_f32_e32 v17, v44, v17
	v_add_f32_e32 v16, v29, v16
	v_add_f32_e32 v17, v45, v17
	v_add_f32_e32 v16, v30, v16
	v_add_f32_e32 v17, v46, v17
	v_add_f32_e32 v16, v31, v16
	v_add_f32_e32 v17, v47, v17
	v_add_f32_e32 v16, v16, v17
	v_add_f32_e32 v167, v0, v16
	v_lshrrev_b32_e32 v16, 2, v159
	v_and_or_b32 v16, v16, 3, v157
	s_andn2_b64 vcc, exec, s[2:3]
	v_mul_u32_u24_e32 v168, 0x140, v16
	s_cbranch_vccnz .LBB0_339
	s_add_i32 s2, 0, 0x18000
	v_lshl_add_u32 v190, v129, 2, s2
	v_mul_u32_u24_e32 v16, 0x1800, v130
	v_and_b32_e32 v18, 15, v159
	v_lshl_or_b32 v150, v18, 4, v16
	v_add_u32_e32 v151, 0x30000, v150
	s_mul_i32 s60, s12, 0x3000000
	s_add_u32 s60, s92, s60
	s_addc_u32 s61, s93, 0
	s_add_u32 s60, s60, s90
	s_addc_u32 s61, s61, s91
	s_add_u32 s60, s60, 0xda42000
	s_addc_u32 s61, s61, 0
	v_readlane_b32 s2, v254, 58
	v_lshlrev_b32_e32 v17, 1, v159
	v_and_b32_e32 v18, 3, v159
	v_add_u32_e32 v16, s2, v168
	v_and_b32_e32 v17, 32, v17
	v_lshlrev_b32_e32 v18, 3, v18
	v_add3_u32 v191, v16, v17, v18
	v_mul_u32_u24_e32 v16, 0x1800, v128
	v_and_b32_e32 v18, 7, v159
	v_lshl_or_b32 v16, v18, 4, v16
	v_add_u32_e32 v152, 0x5f800, v16
	v_mov_b64_e32 v[30:31], v[14:15]
	v_mov_b64_e32 v[46:47], v[14:15]
	v_mov_b64_e32 v[62:63], v[14:15]
	v_mov_b64_e32 v[130:131], v[106:107]
	v_mov_b64_e32 v[134:135], v[98:99]
	s_sub_i32 s22, s23, 63
	s_mov_b32 s23, 2
	s_add_i32 s24, s15, 2
	s_mov_b32 s34, 1
	s_or_b32 s14, s15, 1
	s_not_b32 s25, s15
	s_add_i32 s26, s19, s13
	s_mov_b32 s27, 0
	v_mov_b64_e32 v[28:29], v[12:13]
	v_mov_b64_e32 v[26:27], v[10:11]
	v_mov_b64_e32 v[24:25], v[8:9]
	v_mov_b64_e32 v[22:23], v[6:7]
	v_mov_b64_e32 v[20:21], v[4:5]
	v_mov_b64_e32 v[18:19], v[2:3]
	v_mov_b64_e32 v[16:17], v[0:1]
	v_mov_b64_e32 v[44:45], v[12:13]
	v_mov_b64_e32 v[42:43], v[10:11]
	v_mov_b64_e32 v[40:41], v[8:9]
	v_mov_b64_e32 v[38:39], v[6:7]
	v_mov_b64_e32 v[36:37], v[4:5]
	v_mov_b64_e32 v[34:35], v[2:3]
	v_mov_b64_e32 v[32:33], v[0:1]
	v_mov_b64_e32 v[60:61], v[12:13]
	v_mov_b64_e32 v[58:59], v[10:11]
	v_mov_b64_e32 v[56:57], v[8:9]
	v_mov_b64_e32 v[54:55], v[6:7]
	v_mov_b64_e32 v[52:53], v[4:5]
	v_mov_b64_e32 v[50:51], v[2:3]
	v_mov_b64_e32 v[48:49], v[0:1]
	v_mov_b64_e32 v[128:129], v[104:105]
	v_mov_b64_e32 v[132:133], v[96:97]
	s_cmp_eq_u32 s18, 0
	s_cbranch_scc1 .Lda_entry
	s_barrier
	s_branch .Lda_entry
.LBB0_325:
	v_cvt_pk_bf16_f32 v124, v148, v154
	v_add_f32_e32 v250, v193, v192
	v_add_f32_e32 v251, v209, v208
	v_cvt_pk_bf16_f32 v125, v155, v170
	v_add_f32_e32 v214, v154, v148
	v_add_f32_e32 v215, v205, v204
	v_cvt_pk_bf16_f32 v126, v196, v197
	v_add_f32_e32 v250, v194, v250
	v_add_f32_e32 v251, v220, v251
	v_cvt_pk_bf16_f32 v127, v198, v199
	v_add_f32_e32 v214, v155, v214
	v_add_f32_e32 v215, v206, v215
	v_cvt_pk_bf16_f32 v116, v192, v193
	v_add_f32_e32 v250, v195, v250
	v_add_f32_e32 v251, v221, v251
	v_cvt_pk_bf16_f32 v117, v194, v195
	v_add_f32_e32 v214, v170, v214
	v_add_f32_e32 v215, v207, v215
	v_cvt_pk_bf16_f32 v118, v200, v201
	v_add_f32_e32 v250, v200, v250
	v_add_f32_e32 v251, v226, v251
	v_cvt_pk_bf16_f32 v119, v202, v203
	v_add_f32_e32 v214, v196, v214
	v_add_f32_e32 v215, v222, v215
	v_cvt_pk_bf16_f32 v120, v204, v205
	v_add_f32_e32 v250, v201, v250
	v_add_f32_e32 v251, v227, v251
	v_cvt_pk_bf16_f32 v121, v206, v207
	v_add_f32_e32 v214, v197, v214
	v_add_f32_e32 v215, v223, v215
	v_cvt_pk_bf16_f32 v122, v222, v223
	v_add_f32_e32 v250, v202, v250
	v_add_f32_e32 v251, v228, v251
	v_cvt_pk_bf16_f32 v123, v224, v225
	v_add_f32_e32 v214, v198, v214
	v_add_f32_e32 v215, v224, v215
	v_cvt_pk_bf16_f32 v112, v208, v209
	v_add_f32_e32 v250, v203, v250
	v_add_f32_e32 v251, v229, v251
	v_cvt_pk_bf16_f32 v113, v220, v221
	v_add_f32_e32 v214, v199, v214
	v_add_f32_e32 v215, v225, v215
	v_cvt_pk_bf16_f32 v114, v226, v227
	v_cvt_pk_bf16_f32 v115, v228, v229
	v_add_f32_e32 v250, v250, v251
	v_add_f32_e32 v214, v214, v215
	v_add_f32_e32 v250, v250, v214
	v_add_f32_e32 v167, v167, v250
.Lda_entry:
	v_max3_f32 v148, v64, v65, v66
	v_max3_f32 v154, v72, v73, v74
	v_max3_f32 v155, v80, v81, v82
	v_max3_f32 v170, v88, v89, v90
	v_max3_f32 v148, v148, v67, v68
	v_max3_f32 v154, v154, v75, v76
	v_max3_f32 v155, v155, v83, v84
	v_max3_f32 v170, v170, v91, v92
	v_max3_f32 v148, v148, v69, v70
	v_max3_f32 v154, v154, v77, v78
	v_max3_f32 v155, v155, v85, v86
	v_max3_f32 v170, v170, v93, v94
	v_max_f32_e32 v148, v148, v71
	v_max_f32_e32 v154, v154, v79
	v_max_f32_e32 v155, v155, v87
	v_max_f32_e32 v170, v170, v95
	v_max3_f32 v154, v148, v154, v155
	v_max_f32_e32 v154, v154, v170
	v_mov_b32_e32 v155, v154
	s_cmpk_gt_i32 s26, 0x5e8
	s_cselect_b64 vcc, -1, 0
	v_permlane32_swap_b32_e32 v155, v154
	v_cndmask_b32_e32 v148, 0, v165, vcc
	v_max_f32_e32 v170, v154, v155
	v_add_f32_e32 v154, v148, v170
	v_add_f32_e32 v155, v149, v171
	v_cmp_gt_f32_e32 vcc, v154, v155
	s_mov_b32 s58, 0
	s_cbranch_vccz .LBB0_329
	v_max_f32_e32 v154, v154, v154
	v_max_f32_e32 v155, v149, v149
	v_max_f32_e32 v155, v155, v154
	v_sub_f32_e32 v149, v149, v155
	v_exp_f32_e32 v153, v149
	s_mov_b32 s58, 1
	v_mov_b32_e32 v149, v155
	v_mul_f32_e32 v167, v167, v153
.LBB0_329:
	v_sub_f32_e32 v179, v149, v148
	s_mul_hi_u32 s4, s27, 0xaaaaaaab
	s_lshr_b32 s4, s4, 1
	s_mul_i32 s4, s4, 0xf000
	v_subrev_u32_e32 v250, s4, v191
	v_sub_f32_e32 v148, v64, v179
	v_sub_f32_e32 v192, v80, v179
	v_sub_f32_e32 v154, v65, v179
	v_sub_f32_e32 v193, v81, v179
	v_exp_f32_e32 v148, v148
	v_exp_f32_e32 v192, v192
	v_exp_f32_e32 v154, v154
	v_exp_f32_e32 v193, v193
	v_sub_f32_e32 v155, v66, v179
	v_sub_f32_e32 v194, v82, v179
	v_sub_f32_e32 v170, v67, v179
	v_sub_f32_e32 v195, v83, v179
	v_exp_f32_e32 v155, v155
	v_exp_f32_e32 v194, v194
	v_exp_f32_e32 v170, v170
	v_exp_f32_e32 v195, v195
	v_sub_f32_e32 v196, v68, v179
	v_sub_f32_e32 v200, v84, v179
	v_sub_f32_e32 v197, v69, v179
	v_sub_f32_e32 v201, v85, v179
	ds_read_b64_tr_b16 v[128:129], v250 offset:0
	ds_read_b64_tr_b16 v[130:131], v250 offset:2560
	v_exp_f32_e32 v196, v196
	v_exp_f32_e32 v200, v200
	v_exp_f32_e32 v197, v197
	v_exp_f32_e32 v201, v201
	v_sub_f32_e32 v198, v70, v179
	v_sub_f32_e32 v202, v86, v179
	v_sub_f32_e32 v199, v71, v179
	v_sub_f32_e32 v203, v87, v179
	ds_read_b64_tr_b16 v[132:133], v250 offset:64
	ds_read_b64_tr_b16 v[134:135], v250 offset:2624
	v_exp_f32_e32 v198, v198
	v_exp_f32_e32 v202, v202
	v_exp_f32_e32 v199, v199
	v_exp_f32_e32 v203, v203
	v_sub_f32_e32 v204, v72, v179
	v_sub_f32_e32 v208, v88, v179
	v_sub_f32_e32 v205, v73, v179
	v_sub_f32_e32 v209, v89, v179
	ds_read_b64_tr_b16 v[136:137], v250 offset:128
	ds_read_b64_tr_b16 v[138:139], v250 offset:2688
	v_exp_f32_e32 v204, v204
	v_exp_f32_e32 v208, v208
	v_exp_f32_e32 v205, v205
	v_exp_f32_e32 v209, v209
	v_sub_f32_e32 v206, v74, v179
	v_sub_f32_e32 v220, v90, v179
	v_sub_f32_e32 v207, v75, v179
	v_sub_f32_e32 v221, v91, v179
	ds_read_b64_tr_b16 v[140:141], v250 offset:192
	ds_read_b64_tr_b16 v[142:143], v250 offset:2752
	v_exp_f32_e32 v206, v206
	v_exp_f32_e32 v220, v220
	v_exp_f32_e32 v207, v207
	v_exp_f32_e32 v221, v221
	v_sub_f32_e32 v222, v76, v179
	v_sub_f32_e32 v226, v92, v179
	v_sub_f32_e32 v223, v77, v179
	v_sub_f32_e32 v227, v93, v179
	ds_read_b64_tr_b16 v[230:231], v250 offset:5120
	ds_read_b64_tr_b16 v[232:233], v250 offset:7680
	v_exp_f32_e32 v222, v222
	v_exp_f32_e32 v226, v226
	v_exp_f32_e32 v223, v223
	v_exp_f32_e32 v227, v227
	v_sub_f32_e32 v224, v78, v179
	v_sub_f32_e32 v228, v94, v179
	v_sub_f32_e32 v225, v79, v179
	v_sub_f32_e32 v229, v95, v179
	ds_read_b64_tr_b16 v[234:235], v250 offset:5184
	ds_read_b64_tr_b16 v[236:237], v250 offset:7744
	v_exp_f32_e32 v224, v224
	v_exp_f32_e32 v228, v228
	v_exp_f32_e32 v225, v225
	v_exp_f32_e32 v229, v229
	s_barrier
	s_waitcnt vmcnt(0)
	s_cmp_lt_i32 s34, s15
	s_cselect_b64 s[2:3], -1, 0
	s_cbranch_scc0 .Lda_t_skip_stk
	s_bitcmp1_b32 s34, 0
	s_cselect_b32 s12, 0x4800, 0
	v_add_u32_e32 v215, s12, v163
	ds_write_b128 v215, v[96:99]
	ds_write_b128 v215, v[104:107] offset:9216
.Lda_t_skip_stk:
	s_add_i32 s35, s34, 1
	s_cmp_lt_i32 s35, s24
	s_cbranch_scc0 .Lda_t_skip_stv
	s_mul_hi_u32 s12, s23, 0xaaaaaaab
	s_lshr_b32 s12, s12, 1
	s_mul_i32 s12, s12, 0xffff1000
	s_add_i32 s12, s12, 0x13000
	v_add_u32_e32 v215, s12, v164
	ds_write_b128 v215, v[100:103]
	ds_write_b128 v215, v[108:111] offset:10240

.LBB0_327:
	s_cmp_lt_i32 s35, s24
	s_cselect_b64 s[4:5], -1, 0
	s_and_b64 s[12:13], s[4:5], exec
	s_cselect_b32 s36, s35, s14
	s_lshl_b32 s54, s36, 6
	s_bitcmp1_b32 s36, 0
	s_cselect_b32 s13, 0x4800, 0
	v_add_u32_e32 v214, s13, v166
	s_sub_i32 s12, s22, s54
	s_cmpk_lt_i32 s12, 0x5e9
	s_cbranch_scc0 .Lda_ld_qk
	s_sub_i32 s13, 0, s54
	v_lshl_add_u32 v215, s13, 2, v190
	ds_read2_b32 v[64:65], v215 offset0:128 offset1:127
	ds_read2_b32 v[66:67], v215 offset0:126 offset1:125
	ds_read2_b32 v[68:69], v215 offset0:120 offset1:119
	ds_read2_b32 v[70:71], v215 offset0:118 offset1:117
	ds_read2_b32 v[72:73], v215 offset0:112 offset1:111
	ds_read2_b32 v[74:75], v215 offset0:110 offset1:109
	ds_read2_b32 v[76:77], v215 offset0:104 offset1:103
	ds_read2_b32 v[78:79], v215 offset0:102 offset1:101
	ds_read2_b32 v[80:81], v215 offset0:96 offset1:95
	ds_read2_b32 v[82:83], v215 offset0:94 offset1:93
	ds_read2_b32 v[84:85], v215 offset0:88 offset1:87
	ds_read2_b32 v[86:87], v215 offset0:86 offset1:85
	ds_read2_b32 v[88:89], v215 offset0:80 offset1:79
	ds_read2_b32 v[90:91], v215 offset0:78 offset1:77
	ds_read2_b32 v[92:93], v215 offset0:72 offset1:71
	ds_read2_b32 v[94:95], v215 offset0:70 offset1:69
.Lda_ld_qk:
	ds_read_b128 v[246:249], v162
	ds_read_b128 v[178:181], v214
	s_waitcnt lgkmcnt(12)
	v_mfma_f32_32x32x16_bf16 v[48:63], v[128:131], v[124:127], v[48:63]
	ds_read_b64_tr_b16 v[238:239], v250 offset:5248
	ds_read_b64_tr_b16 v[240:241], v250 offset:7808
	s_waitcnt lgkmcnt(12)
	v_mfma_f32_32x32x16_bf16 v[32:47], v[132:135], v[124:127], v[32:47]
	ds_read_b64_tr_b16 v[242:243], v250 offset:5312
	ds_read_b64_tr_b16 v[244:245], v250 offset:7872
	s_waitcnt lgkmcnt(12)
	v_mfma_f32_32x32x16_bf16 v[16:31], v[136:139], v[124:127], v[16:31]
	ds_read_b64_tr_b16 v[128:129], v250 offset:10240
	ds_read_b64_tr_b16 v[130:131], v250 offset:12800
	s_waitcnt lgkmcnt(12)
	v_mfma_f32_32x32x16_bf16 v[0:15], v[140:143], v[124:127], v[0:15]
	ds_read_b64_tr_b16 v[132:133], v250 offset:10304
	ds_read_b64_tr_b16 v[134:135], v250 offset:12864
	s_waitcnt lgkmcnt(12)
	v_mfma_f32_32x32x16_bf16 v[48:63], v[230:233], v[120:123], v[48:63]
	ds_read_b64_tr_b16 v[136:137], v250 offset:10368
	ds_read_b64_tr_b16 v[138:139], v250 offset:12928
	s_waitcnt lgkmcnt(12)
	v_mfma_f32_32x32x16_bf16 v[32:47], v[234:237], v[120:123], v[32:47]
	ds_read_b64_tr_b16 v[140:141], v250 offset:10432
	ds_read_b64_tr_b16 v[142:143], v250 offset:12992
	s_waitcnt lgkmcnt(10)
	v_mfma_f32_32x32x16_bf16 v[16:31], v[238:241], v[120:123], v[16:31]
	ds_read_b64_tr_b16 v[230:231], v250 offset:15360
	ds_read_b64_tr_b16 v[232:233], v250 offset:17920
	s_waitcnt lgkmcnt(10)
	v_mfma_f32_32x32x16_bf16 v[0:15], v[242:245], v[120:123], v[0:15]
	ds_read_b64_tr_b16 v[234:235], v250 offset:15424
	ds_read_b64_tr_b16 v[236:237], v250 offset:17984
	s_waitcnt lgkmcnt(10)
	v_mfma_f32_32x32x16_bf16 v[48:63], v[128:131], v[116:119], v[48:63]
	ds_read_b64_tr_b16 v[238:239], v250 offset:15488
	ds_read_b64_tr_b16 v[240:241], v250 offset:18048
	ds_read_b128 v[128:131], v214 offset:4608
	s_waitcnt lgkmcnt(11)
	v_mfma_f32_32x32x16_bf16 v[32:47], v[132:135], v[116:119], v[32:47]
	ds_read_b64_tr_b16 v[242:243], v250 offset:15552
	ds_read_b64_tr_b16 v[244:245], v250 offset:18112
	ds_read_b128 v[132:135], v162 offset:1024
	s_waitcnt lgkmcnt(12)
	v_mfma_f32_32x32x16_bf16 v[16:31], v[136:139], v[116:119], v[16:31]
	ds_read_b128 v[136:139], v214 offset:32
	s_waitcnt lgkmcnt(11)
	v_mfma_f32_32x32x16_bf16 v[0:15], v[140:143], v[116:119], v[0:15]
	ds_read_b128 v[140:143], v214 offset:4640
	s_waitcnt lgkmcnt(10)
	v_mfma_f32_32x32x16_bf16 v[48:63], v[230:233], v[112:115], v[48:63]
	ds_read_b128 v[230:233], v162 offset:2048
	s_waitcnt lgkmcnt(9)
	v_mfma_f32_32x32x16_bf16 v[32:47], v[234:237], v[112:115], v[32:47]
	ds_read_b128 v[234:237], v214 offset:64
	s_waitcnt lgkmcnt(8)
	v_mfma_f32_32x32x16_bf16 v[16:31], v[238:241], v[112:115], v[16:31]
	ds_read_b128 v[238:241], v214 offset:4672
	s_waitcnt lgkmcnt(6)
	v_mfma_f32_32x32x16_bf16 v[0:15], v[242:245], v[112:115], v[0:15]
	ds_read_b128 v[242:245], v162 offset:3072
	s_cmpk_lt_i32 s12, 0x5e9
	s_cbranch_scc0 .Lda_mm_far
	v_mfma_f32_32x32x16_bf16 v[64:79], v[178:181], v[246:249], v[64:79]
	v_mfma_f32_32x32x16_bf16 v[80:95], v[128:131], v[246:249], v[80:95]
	s_branch .Lda_mm_rest
.Lda_mm_far:
	v_mfma_f32_32x32x16_bf16 v[64:79], v[178:181], v[246:249], 0
	v_mfma_f32_32x32x16_bf16 v[80:95], v[128:131], v[246:249], 0
.Lda_mm_rest:
	ds_read_b128 v[178:181], v214 offset:96
	ds_read_b128 v[246:249], v214 offset:4704
	s_waitcnt lgkmcnt(7)
	v_mfma_f32_32x32x16_bf16 v[64:79], v[136:139], v[132:135], v[64:79]
	s_waitcnt lgkmcnt(6)
	v_mfma_f32_32x32x16_bf16 v[80:95], v[140:143], v[132:135], v[80:95]
	s_waitcnt lgkmcnt(4)
	v_mfma_f32_32x32x16_bf16 v[64:79], v[234:237], v[230:233], v[64:79]
	s_waitcnt lgkmcnt(3)
	v_mfma_f32_32x32x16_bf16 v[80:95], v[238:241], v[230:233], v[80:95]
	s_waitcnt lgkmcnt(1)
	v_mfma_f32_32x32x16_bf16 v[64:79], v[178:181], v[242:245], v[64:79]
	s_waitcnt lgkmcnt(0)
	v_mfma_f32_32x32x16_bf16 v[80:95], v[246:249], v[242:245], v[80:95]
	s_cmp_lg_u32 s58, 0
	s_cbranch_scc0 .Lda_noscale
	s_nop 7
	v_mul_f32_e32 v63, v63, v153
	v_mul_f32_e32 v62, v62, v153
	v_mul_f32_e32 v61, v61, v153
	v_mul_f32_e32 v60, v60, v153
	v_mul_f32_e32 v59, v59, v153
	v_mul_f32_e32 v58, v58, v153
	v_mul_f32_e32 v57, v57, v153
	v_mul_f32_e32 v56, v56, v153
	v_mul_f32_e32 v55, v55, v153
	v_mul_f32_e32 v54, v54, v153
	v_mul_f32_e32 v53, v53, v153
	v_mul_f32_e32 v52, v52, v153
	v_mul_f32_e32 v51, v51, v153
	v_mul_f32_e32 v50, v50, v153
	v_mul_f32_e32 v49, v49, v153
	v_mul_f32_e32 v48, v48, v153
	v_mul_f32_e32 v47, v47, v153
	v_mul_f32_e32 v46, v46, v153
	v_mul_f32_e32 v45, v45, v153
	v_mul_f32_e32 v44, v44, v153
	v_mul_f32_e32 v43, v43, v153
	v_mul_f32_e32 v42, v42, v153
	v_mul_f32_e32 v41, v41, v153
	v_mul_f32_e32 v40, v40, v153
	v_mul_f32_e32 v39, v39, v153
	v_mul_f32_e32 v38, v38, v153
	v_mul_f32_e32 v37, v37, v153
	v_mul_f32_e32 v36, v36, v153
	v_mul_f32_e32 v35, v35, v153
	v_mul_f32_e32 v34, v34, v153
	v_mul_f32_e32 v33, v33, v153
	v_mul_f32_e32 v32, v32, v153
	v_mul_f32_e32 v31, v31, v153
	v_mul_f32_e32 v30, v30, v153
	v_mul_f32_e32 v29, v29, v153
	v_mul_f32_e32 v28, v28, v153
	v_mul_f32_e32 v27, v27, v153
	v_mul_f32_e32 v26, v26, v153
	v_mul_f32_e32 v25, v25, v153
	v_mul_f32_e32 v24, v24, v153
	v_mul_f32_e32 v23, v23, v153
	v_mul_f32_e32 v22, v22, v153
	v_mul_f32_e32 v21, v21, v153
	v_mul_f32_e32 v20, v20, v153
	v_mul_f32_e32 v19, v19, v153
	v_mul_f32_e32 v18, v18, v153
	v_mul_f32_e32 v17, v17, v153
	v_mul_f32_e32 v16, v16, v153
	v_mul_f32_e32 v15, v15, v153
	v_mul_f32_e32 v14, v14, v153
	v_mul_f32_e32 v13, v13, v153
	v_mul_f32_e32 v12, v12, v153
	v_mul_f32_e32 v11, v11, v153
	v_mul_f32_e32 v10, v10, v153
	v_mul_f32_e32 v9, v9, v153
	v_mul_f32_e32 v8, v8, v153
	v_mul_f32_e32 v7, v7, v153
	v_mul_f32_e32 v6, v6, v153
	v_mul_f32_e32 v5, v5, v153
	v_mul_f32_e32 v4, v4, v153
	v_mul_f32_e32 v3, v3, v153
	v_mul_f32_e32 v2, v2, v153
	v_mul_f32_e32 v1, v1, v153
	v_mul_f32_e32 v0, v0, v153
.Lda_noscale:
	s_add_i32 s23, s23, 1
	s_add_i32 s2, s25, s35
	s_add_i32 s27, s27, 1
	s_sub_i32 s26, s26, 64
	s_add_u32 s60, s60, s88
	s_addc_u32 s61, s61, s89
	v_add_u32_e32 v164, 0x5000, v164
	v_add_u32_e32 v191, 0x5000, v191
	s_cmp_eq_u32 s2, 1
	s_waitcnt lgkmcnt(0)
	s_barrier
	s_cbranch_scc1 .LBB0_340
	s_mov_b32 s34, s35
	s_branch .LBB0_325

.LBB0_340:
	s_cmp_lg_u32 s18, 0
	s_cbranch_scc1 .Lda_exit_b
	s_barrier
.Lda_exit_b:
	v_cvt_pk_bf16_f32 v124, v148, v154
	v_add_f32_e32 v250, v193, v192
	v_add_f32_e32 v251, v209, v208
	v_cvt_pk_bf16_f32 v125, v155, v170
	v_add_f32_e32 v214, v154, v148
	v_add_f32_e32 v215, v205, v204
	v_cvt_pk_bf16_f32 v126, v196, v197
	v_add_f32_e32 v250, v194, v250
	v_add_f32_e32 v251, v220, v251
	v_cvt_pk_bf16_f32 v127, v198, v199
	v_add_f32_e32 v214, v155, v214
	v_add_f32_e32 v215, v206, v215
	v_cvt_pk_bf16_f32 v116, v192, v193
	v_add_f32_e32 v250, v195, v250
	v_add_f32_e32 v251, v221, v251
	v_cvt_pk_bf16_f32 v117, v194, v195
	v_add_f32_e32 v214, v170, v214
	v_add_f32_e32 v215, v207, v215
	v_cvt_pk_bf16_f32 v118, v200, v201
	v_add_f32_e32 v250, v200, v250
	v_add_f32_e32 v251, v226, v251
	v_cvt_pk_bf16_f32 v119, v202, v203
	v_add_f32_e32 v214, v196, v214
	v_add_f32_e32 v215, v222, v215
	v_cvt_pk_bf16_f32 v120, v204, v205
	v_add_f32_e32 v250, v201, v250
	v_add_f32_e32 v251, v227, v251
	v_cvt_pk_bf16_f32 v121, v206, v207
	v_add_f32_e32 v214, v197, v214
	v_add_f32_e32 v215, v223, v215
	v_cvt_pk_bf16_f32 v122, v222, v223
	v_add_f32_e32 v250, v202, v250
	v_add_f32_e32 v251, v228, v251
	v_cvt_pk_bf16_f32 v123, v224, v225
	v_add_f32_e32 v214, v198, v214
	v_add_f32_e32 v215, v224, v215
	v_cvt_pk_bf16_f32 v112, v208, v209
	v_add_f32_e32 v250, v203, v250
	v_add_f32_e32 v251, v229, v251
	v_cvt_pk_bf16_f32 v113, v220, v221
	v_add_f32_e32 v214, v199, v214
	v_add_f32_e32 v215, v225, v215
	v_cvt_pk_bf16_f32 v114, v226, v227
	v_cvt_pk_bf16_f32 v115, v228, v229
	v_add_f32_e32 v250, v250, v251
	v_add_f32_e32 v214, v214, v215
	v_add_f32_e32 v250, v250, v214
	v_add_f32_e32 v167, v167, v250
	s_waitcnt vmcnt(1)
	v_mov_b64_e32 v[96:97], v[132:133]
	s_waitcnt vmcnt(0)
	v_mov_b64_e32 v[104:105], v[128:129]
	v_mov_b64_e32 v[100:101], v[140:141]
	v_mov_b64_e32 v[108:109], v[136:137]
	v_readlane_b32 s24, v254, 62
	v_readlane_b32 s26, v255, 0
	v_readlane_b32 s34, v255, 2
	v_mov_b64_e32 v[98:99], v[134:135]
	v_mov_b64_e32 v[106:107], v[130:131]
	v_mov_b64_e32 v[102:103], v[142:143]
	v_mov_b64_e32 v[110:111], v[138:139]
	v_readlane_b32 s25, v254, 63
	v_readlane_b32 s27, v255, 1
	v_readlane_b32 s35, v255, 3
